# MIX order selector bit3 (within-XCD half of WGs attention-first) instead of bit0
# speedup vs baseline: 1.0215x; 1.0068x over previous
; #define GEMMCALL if (0)
; #define FRESH_TID() asm volatile("" : "+v"(tid))
; __global__ void __launch_bounds__(NTHREADS, 2) mega(Params p) {
;     ...
;             for (int rep = 0; rep < REP_FOUR; ++rep) { FRESH_TID(); fft_phase(p, lds, tid); }
;             if (l == 0) {
;                 pg8::Gemm g{(const bf16_t*)(ws + WS_CTC), (const bf16_t*)(ws + WS_ZTC), 256, 2048, 512}; pg8::StaticOrder S; S.init(256, 2048, G, (int)blockIdx.x);
;                 EpiStore<0> E{MIX + (size_t)MX * KOUT + 512, KOUT, (size_t)256 * KOUT};
;                 GEMMCALL pg8::gemm_phase<EpiStore<0>, pg8::StaticOrder, true, true>(lds, g, S, E);
;             }
;             __syncthreads();
;             for (int rep = 0; rep < REP_ATTN; ++rep) { FRESH_TID(); attn_phase(p, l, lds, tid); }
.LBB0_452:
	s_or_b64 exec, exec, s[0:1]
	v_readlane_b32 s0, v254, 56
	v_readlane_b32 s1, v254, 57
	s_andn2_b64 vcc, exec, s[0:1]
	s_waitcnt lgkmcnt(0)
	s_barrier
	s_mov_b32 s68, 0
	s_bitcmp1_b32 s2, 3
	s_cbranch_scc0 .Lmix_norm
	s_mov_b32 s68, 1
	s_branch .LBB0_455
